# v10 + scan: decay-table loads issued together (were 8 serial round trips); dilation-group merge loop software-pipelined (24 loads in flight per 4 units, was 2 exposed round trips per unit)
# speedup vs baseline: 1.0011x; 1.0011x over previous
; #define LAS __attribute__((address_space(3)))
; #define BAR_LDS() do { asm volatile("s_waitcnt lgkmcnt(0)" ::: "memory"); __builtin_amdgcn_s_barrier(); asm volatile("" ::: "memory"); } while (0)
; template <int KW, int NC, bool F8> __device__ __forceinline__ void scan_chain(const Ctx& X, unsigned char* p, const float* dp, int dir, int koff) {
;     typedef typename ScanVec<F8>::T V; constexpr int CS = 128 * KW * (F8 ? 1 : 2); const lptr DT = X.lds;
;     V u[8];
; #pragma unroll
;     for (int j = 0; j < 8; ++j) u[j] = *(const V*)(p + (size_t)(dir ? NC - 1 - j : j) * CS);
;     BAR_LDS();
; #pragma unroll
;     for (int i = 0; i < NC * KW / 4 / NTHR; ++i) *(LAS f32x4*)(DT + (X.tid + NTHR * i) * 16) = *(const f32x4*)(dp + (size_t)(X.tid + NTHR * i) * 4);
;     BAR_LDS();
;     float S[8];
; #pragma unroll
;     for (int i = 0; i < 8; ++i) S[i] = 0.f;
.LBB0_384:
	s_cmpk_gt_i32 s23, 0x5f
	s_mov_b64 s[0:1], -1
	s_cbranch_scc0 .LBB0_388
	s_add_i32 s0, s23, 0xffffffa0
	s_lshr_b32 s34, s0, 1
	s_lshl_b32 s0, s23, 9
	s_and_b32 s0, s0, 0x200
	v_add_lshl_u32 v2, s0, v34, 3
	s_lshl_b64 s[0:1], s[34:35], 20
	s_add_u32 s0, s14, s0
	v_ashrrev_i32_e32 v3, 31, v2
	s_addc_u32 s1, s15, s1
	v_lshl_add_u64 v[52:53], v[2:3], 1, s[0:1]
	s_lshl_b64 s[0:1], s[34:35], 14
	s_add_u32 s12, s16, s0
	s_addc_u32 s13, s17, s1
	s_bfe_i32 s1, s23, 0x10001
	s_and_b32 s0, s23, 2
	s_and_b32 s4, s1, 0xfc000
	s_cmp_eq_u32 s0, 0
	s_mov_b32 s5, 0
	s_cselect_b64 s[0:1], -1, 0
	v_lshl_add_u64 v[2:3], v[52:53], 0, s[4:5]
	s_and_b64 s[24:25], s[0:1], exec
	s_mov_b32 s4, 0xf8000
	s_cselect_b32 s4, 0x4000, s4
	global_load_dwordx4 v[30:33], v[2:3], off
	v_lshl_add_u64 v[2:3], v[52:53], 0, s[4:5]
	s_mov_b32 s4, 0xf4000
	s_cselect_b32 s4, 0x8000, s4
	global_load_dwordx4 v[26:29], v[2:3], off
	v_lshl_add_u64 v[2:3], v[52:53], 0, s[4:5]
	s_mov_b32 s4, 0xf0000
	s_cselect_b32 s4, 0xc000, s4
	global_load_dwordx4 v[22:25], v[2:3], off
	v_lshl_add_u64 v[2:3], v[52:53], 0, s[4:5]
	s_mov_b32 s4, 0xec000
	s_cselect_b32 s4, 0x10000, s4
	global_load_dwordx4 v[14:17], v[2:3], off
	v_lshl_add_u64 v[2:3], v[52:53], 0, s[4:5]
	s_mov_b32 s4, 0xe8000
	s_cselect_b32 s4, 0x14000, s4
	global_load_dwordx4 v[18:21], v[2:3], off
	v_lshl_add_u64 v[2:3], v[52:53], 0, s[4:5]
	s_mov_b32 s4, 0xe4000
	s_cselect_b32 s4, 0x18000, s4
	global_load_dwordx4 v[10:13], v[2:3], off
	v_lshl_add_u64 v[2:3], v[52:53], 0, s[4:5]
	s_mov_b32 s4, 0xe0000
	s_cselect_b32 s4, 0x1c000, s4
	v_lshl_add_u64 v[6:7], v[52:53], 0, s[4:5]
	global_load_dwordx4 v[2:5], v[2:3], off
	v_lshl_add_u64 v[164:165], s[12:13], 0, v[36:37]
	global_load_dwordx4 v[6:9], v[6:7], off
	s_waitcnt lgkmcnt(0)
	s_barrier
	global_load_dwordx4 v[164:167], v[164:165], off
	v_lshl_add_u64 v[168:169], s[12:13], 0, v[38:39]
	global_load_dwordx4 v[168:171], v[168:169], off
	s_cselect_b32 s4, 8, -8
	s_mov_b32 s12, 56
	s_waitcnt vmcnt(1)
	ds_write_b128 v69, v[164:167]
	s_waitcnt vmcnt(0)
	ds_write_b128 v70, v[168:171]
	s_waitcnt lgkmcnt(0)
	s_barrier
	v_mov_b32_e32 v54, 0
	v_mov_b32_e32 v55, v54
	v_mov_b32_e32 v56, v54
	v_mov_b32_e32 v57, v54
	v_mov_b32_e32 v60, v54
	v_mov_b32_e32 v61, v54
	v_mov_b32_e32 v58, v54
	v_mov_b32_e32 v59, v54

; #define LAS __attribute__((address_space(3)))
; #define BAR_LDS() do { asm volatile("s_waitcnt lgkmcnt(0)" ::: "memory"); __builtin_amdgcn_s_barrier(); asm volatile("" ::: "memory"); } while (0)
; template <int KW, int NC, bool F8> __device__ __forceinline__ void scan_chain(const Ctx& X, unsigned char* p, const float* dp, int dir, int koff) {
;     typedef typename ScanVec<F8>::T V; constexpr int CS = 128 * KW * (F8 ? 1 : 2); const lptr DT = X.lds;
;     V u[8];
; #pragma unroll
;     for (int j = 0; j < 8; ++j) u[j] = *(const V*)(p + (size_t)(dir ? NC - 1 - j : j) * CS);
;     BAR_LDS();
; #pragma unroll
;     for (int i = 0; i < NC * KW / 4 / NTHR; ++i) *(LAS f32x4*)(DT + (X.tid + NTHR * i) * 16) = *(const f32x4*)(dp + (size_t)(X.tid + NTHR * i) * 4);
;     BAR_LDS();
;     float S[8];
; #pragma unroll
;     for (int i = 0; i < 8; ++i) S[i] = 0.f;
; __device__ __forceinline__ void scan_phase(const Ctx& X) {
;     ...
;             scan_chain<128, NCH, true>(X, X.ws + WS_SHG + (size_t)chain * NCH * 16384 + e * 8, (const float*)(X.ws + WS_DHG) + (size_t)chain * NCH * 128, chain & 1, (e & 15) * 8); }
.LBB0_388:
	s_and_b64 vcc, exec, s[0:1]
	s_cbranch_vccz .LBB0_383
	s_ashr_i32 s0, s23, 2
	s_lshl_b32 s1, s23, 9
	s_and_b32 s12, s1, 0x600
	s_ashr_i32 s1, s0, 31
	s_lshl_b64 s[4:5], s[0:1], 21
	s_add_u32 s4, s18, s4
	s_addc_u32 s5, s19, s5
	s_lshl_b64 s[0:1], s[0:1], 16
	v_add_lshl_u32 v2, s12, v34, 3
	s_add_u32 s12, s21, s0
	v_ashrrev_i32_e32 v3, 31, v2
	s_addc_u32 s13, s22, s1
	s_bfe_i32 s1, s23, 0x10002
	v_lshl_add_u64 v[2:3], s[4:5], 0, v[2:3]
	s_and_b32 s0, s23, 4
	s_and_b32 s4, s1, 0x1fc000
	s_cmp_eq_u32 s0, 0
	s_mov_b32 s5, 0
	s_cselect_b64 s[0:1], -1, 0
	v_lshl_add_u64 v[4:5], v[2:3], 0, s[4:5]
	s_and_b64 s[24:25], s[0:1], exec
	s_mov_b32 s4, 0x1f8000
	s_cselect_b32 s4, 0x4000, s4
	global_load_dwordx2 v[16:17], v[4:5], off
	v_lshl_add_u64 v[4:5], v[2:3], 0, s[4:5]
	s_mov_b32 s4, 0x1f4000
	s_cselect_b32 s4, 0x8000, s4
	global_load_dwordx2 v[18:19], v[4:5], off
	v_lshl_add_u64 v[4:5], v[2:3], 0, s[4:5]
	s_mov_b32 s4, 0x1f0000
	s_cselect_b32 s4, 0xc000, s4
	global_load_dwordx2 v[12:13], v[4:5], off
	v_lshl_add_u64 v[4:5], v[2:3], 0, s[4:5]
	s_mov_b32 s4, 0x1ec000
	s_cselect_b32 s4, 0x10000, s4
	global_load_dwordx2 v[14:15], v[4:5], off
	v_lshl_add_u64 v[4:5], v[2:3], 0, s[4:5]
	s_mov_b32 s4, 0x1e8000
	s_cselect_b32 s4, 0x14000, s4
	global_load_dwordx2 v[10:11], v[4:5], off
	v_lshl_add_u64 v[4:5], v[2:3], 0, s[4:5]
	s_mov_b32 s4, 0x1e4000
	s_cselect_b32 s4, 0x18000, s4
	global_load_dwordx2 v[8:9], v[4:5], off
	v_lshl_add_u64 v[4:5], v[2:3], 0, s[4:5]
	s_mov_b32 s4, 0x1e0000
	s_cselect_b32 s4, 0x1c000, s4
	v_lshl_add_u64 v[6:7], v[2:3], 0, s[4:5]
	global_load_dwordx2 v[4:5], v[4:5], off
	v_lshl_add_u64 v[164:165], s[12:13], 0, v[36:37]
	global_load_dwordx2 v[6:7], v[6:7], off
	s_waitcnt lgkmcnt(0)
	s_barrier
	global_load_dwordx4 v[164:167], v[164:165], off
	v_lshl_add_u64 v[168:169], s[12:13], 0, v[38:39]
	global_load_dwordx4 v[168:171], v[168:169], off
	v_lshl_add_u64 v[172:173], s[12:13], 0, v[40:41]
	global_load_dwordx4 v[172:175], v[172:173], off
	v_lshl_add_u64 v[176:177], s[12:13], 0, v[42:43]
	global_load_dwordx4 v[176:179], v[176:177], off
	v_lshl_add_u64 v[180:181], s[12:13], 0, v[44:45]
	global_load_dwordx4 v[180:183], v[180:181], off
	v_lshl_add_u64 v[184:185], s[12:13], 0, v[46:47]
	global_load_dwordx4 v[184:187], v[184:185], off
	v_lshl_add_u64 v[188:189], s[12:13], 0, v[48:49]
	global_load_dwordx4 v[188:191], v[188:189], off
	v_lshl_add_u64 v[200:201], s[12:13], 0, v[50:51]
	global_load_dwordx4 v[200:203], v[200:201], off
	v_mov_b32_e32 v24, 0
	s_cselect_b32 s4, 8, -8
	v_mov_b32_e32 v25, v24
	v_mov_b32_e32 v26, v24
	v_mov_b32_e32 v27, v24
	v_mov_b32_e32 v28, v24
	s_movk_i32 s12, 0x78
	s_waitcnt vmcnt(7)
	ds_write_b128 v69, v[164:167]
	s_waitcnt vmcnt(6)
	ds_write_b128 v70, v[168:171]
	s_waitcnt vmcnt(5)
	ds_write_b128 v63, v[172:175]
	s_waitcnt vmcnt(4)
	ds_write_b128 v64, v[176:179]
	s_waitcnt vmcnt(3)
	ds_write_b128 v65, v[180:183]
	s_waitcnt vmcnt(2)
	ds_write_b128 v66, v[184:187]
	s_waitcnt vmcnt(1)
	ds_write_b128 v67, v[188:191]
	s_waitcnt vmcnt(0)
	ds_write_b128 v68, v[200:203]
	s_waitcnt lgkmcnt(0)
	s_barrier
	v_mov_b32_e32 v20, v24
	v_mov_b32_e32 v21, v24
	v_mov_b32_e32 v22, v24
	v_mov_b32_e32 v23, v24

; __device__ __forceinline__ float bf2f(unsigned h) { return __uint_as_float(h << 16); }
; __device__ __forceinline__ unsigned pk2(float lo, float hi) { return pg8::cvt_pk_bf16(lo, hi); }
; __device__ __forceinline__ void dil_merge_units(const Ctx& X, const bf16* H, bf16* Y, int u0, int u1) {
;     const float* LSE = (const float*)(X.ws + WS_LSE);
;     for (int ub = u0; ub < u1; ub += 4)
; #pragma unroll
;     for (int p = 0; p < 4; ++p) { const int un = min(ub + p, u1 - 1); const int slot = (X.tid >> 4) & 3, c8 = X.tid & 15; const size_t m = (size_t)un * 8 + (X.tid >> 6);
;         const float l0 = LSE[(0 * (size_t)M + m) * 4 + slot], l1 = LSE[(1 * (size_t)M + m) * 4 + slot], l2 = LSE[(2 * (size_t)M + m) * 4 + slot]; const float mxl = fmaxf(l0, fmaxf(l1, l2));
;         const float e0 = __expf(l0 - mxl), e1 = __expf(l1 - mxl), e2 = __expf(l2 - mxl), inv = __builtin_amdgcn_rcpf(e0 + e1 + e2); const float w[3] = {e0 * inv, e1 * inv, e2 * inv};
;         float acc[8];
; #pragma unroll
;         for (int e = 0; e < 8; ++e) acc[e] = 0.f;
; #pragma unroll
;         for (int g = 0; g < 3; ++g) { const int sh = 2 * g, t = (int)(m & 8191); const size_t pm = (m & ~(size_t)8191) + (size_t)(((t & ((1 << sh) - 1)) << (13 - sh)) + (t >> sh));
;             const v4u ow = *(const v4u*)hptr(H, pm, C_DIL + (3 * g) * 512 + slot * 128 + 8 * c8);
;             acc[0] += w[g] * bf2f(ow.x & 0xffffu); acc[1] += w[g] * bf2f(ow.x >> 16); acc[2] += w[g] * bf2f(ow.y & 0xffffu); acc[3] += w[g] * bf2f(ow.y >> 16);
;             acc[4] += w[g] * bf2f(ow.z & 0xffffu); acc[5] += w[g] * bf2f(ow.z >> 16); acc[6] += w[g] * bf2f(ow.w & 0xffffu); acc[7] += w[g] * bf2f(ow.w >> 16); }
;         v4u o; o.x = pk2(acc[0], acc[1]); o.y = pk2(acc[2], acc[3]); o.z = pk2(acc[4], acc[5]); o.w = pk2(acc[6], acc[7]);
;         *(v4u*)(Y + m * D + 1536 + slot * 128 + 8 * c8) = o; }
.LBB0_411:
	s_cmp_ge_i32 s12, s18
	s_cbranch_scc1 .LBB0_414
	v_bfe_u32 v2, v23, 4, 2
	v_lshlrev_b32_e32 v158, 22, v2
	v_lshlrev_b32_e32 v3, 4, v23
	v_lshl_add_u64 v[4:5], s[14:15], 0, v[158:159]
	v_and_b32_e32 v158, 0xf0, v3
	v_lshl_add_u64 v[4:5], v[4:5], 0, v[158:159]
	s_mov_b64 s[14:15], 0xc000000
	v_lshl_add_u64 v[12:13], v[4:5], 0, s[14:15]
	s_mov_b64 s[14:15], 0xf000000
	v_lshl_add_u64 v[14:15], v[4:5], 0, s[14:15]
	s_mov_b64 s[14:15], 0x12000000
	v_lshl_add_u64 v[16:17], v[4:5], 0, s[14:15]
	v_lshlrev_b32_e32 v4, 8, v2
	v_mov_b32_e32 v5, v159
	s_add_u32 s16, s16, 0x500000
	v_ashrrev_i32_e32 v10, 6, v23
	v_lshl_add_u64 v[4:5], s[4:5], 0, v[4:5]
	s_addc_u32 s17, s17, 0
	s_add_i32 s0, s18, -1
	v_ashrrev_i32_e32 v11, 31, v10
	v_lshl_add_u64 v[18:19], v[4:5], 0, v[158:159]
	v_lshlrev_b32_e32 v158, 2, v2
	s_mov_b32 s13, 0x40000
	s_mov_b32 s14, 0x80000
	s_mov_b64 s[98:99], 0x40000
	s_mov_b64 s[100:101], 0x80000
.LBB0_413:
	s_min_i32 s4, s12, s0
	s_ashr_i32 s5, s4, 31
	v_lshl_add_u64 v[36:37], s[4:5], 3, v[10:11]
	v_lshl_add_u64 v[38:39], v[36:37], 4, s[16:17]
	v_lshl_add_u64 v[38:39], v[38:39], 0, v[158:159]
	global_load_dword v44, v[38:39], off
	v_lshl_add_u64 v[40:41], v[38:39], 0, s[98:99]
	global_load_dword v45, v[40:41], off
	v_lshl_add_u64 v[40:41], v[38:39], 0, s[100:101]
	global_load_dword v46, v[40:41], off
	v_lshlrev_b64 v[40:41], 8, v[36:37]
	v_lshl_add_u64 v[40:41], v[12:13], 0, v[40:41]
	global_load_dwordx4 v[54:57], v[40:41], off
	v_and_b32_e32 v43, 0xffffe000, v36
	v_lshlrev_b32_e32 v40, 11, v36
	v_and_b32_e32 v40, 0x1800, v40
	v_bfe_u32 v42, v36, 2, 11
	v_or3_b32 v40, v40, v42, v43
	v_and_b32_e32 v41, 0xffffff, v37
	v_lshlrev_b64 v[40:41], 8, v[40:41]
	v_lshl_add_u64 v[40:41], v[14:15], 0, v[40:41]
	global_load_dwordx4 v[58:61], v[40:41], off
	v_lshlrev_b32_e32 v40, 9, v36
	v_and_b32_e32 v40, 0x1e00, v40
	v_bfe_u32 v42, v36, 4, 9
	v_or3_b32 v40, v40, v42, v43
	v_and_b32_e32 v41, 0xffffff, v37
	v_lshlrev_b64 v[40:41], 8, v[40:41]
	v_lshl_add_u64 v[40:41], v[16:17], 0, v[40:41]
	global_load_dwordx4 v[62:65], v[40:41], off
	s_add_i32 s1, s12, 1
	s_min_i32 s4, s1, s0
	s_ashr_i32 s5, s4, 31
	v_lshl_add_u64 v[66:67], s[4:5], 3, v[10:11]
	v_lshl_add_u64 v[68:69], v[66:67], 4, s[16:17]
	v_lshl_add_u64 v[68:69], v[68:69], 0, v[158:159]
	global_load_dword v74, v[68:69], off
	v_lshl_add_u64 v[70:71], v[68:69], 0, s[98:99]
	global_load_dword v75, v[70:71], off
	v_lshl_add_u64 v[70:71], v[68:69], 0, s[100:101]
	global_load_dword v76, v[70:71], off
	v_lshlrev_b64 v[70:71], 8, v[66:67]
	v_lshl_add_u64 v[70:71], v[12:13], 0, v[70:71]
	global_load_dwordx4 v[84:87], v[70:71], off
	v_and_b32_e32 v73, 0xffffe000, v66
	v_lshlrev_b32_e32 v70, 11, v66
	v_and_b32_e32 v70, 0x1800, v70
	v_bfe_u32 v72, v66, 2, 11
	v_or3_b32 v70, v70, v72, v73
	v_and_b32_e32 v71, 0xffffff, v67
	v_lshlrev_b64 v[70:71], 8, v[70:71]
	v_lshl_add_u64 v[70:71], v[14:15], 0, v[70:71]
	global_load_dwordx4 v[88:91], v[70:71], off
	v_lshlrev_b32_e32 v70, 9, v66
	v_and_b32_e32 v70, 0x1e00, v70
	v_bfe_u32 v72, v66, 4, 9
	v_or3_b32 v70, v70, v72, v73
	v_and_b32_e32 v71, 0xffffff, v67
	v_lshlrev_b64 v[70:71], 8, v[70:71]
	v_lshl_add_u64 v[70:71], v[16:17], 0, v[70:71]
	global_load_dwordx4 v[92:95], v[70:71], off
	s_add_i32 s1, s12, 2
	s_min_i32 s4, s1, s0
	s_ashr_i32 s5, s4, 31
	v_lshl_add_u64 v[114:115], s[4:5], 3, v[10:11]
	v_lshl_add_u64 v[116:117], v[114:115], 4, s[16:17]
	v_lshl_add_u64 v[116:117], v[116:117], 0, v[158:159]
	global_load_dword v122, v[116:117], off
	v_lshl_add_u64 v[118:119], v[116:117], 0, s[98:99]
	global_load_dword v123, v[118:119], off
	v_lshl_add_u64 v[118:119], v[116:117], 0, s[100:101]
	global_load_dword v124, v[118:119], off
	v_lshlrev_b64 v[118:119], 8, v[114:115]
	v_lshl_add_u64 v[118:119], v[12:13], 0, v[118:119]
	global_load_dwordx4 v[132:135], v[118:119], off
	v_and_b32_e32 v121, 0xffffe000, v114
	v_lshlrev_b32_e32 v118, 11, v114
	v_and_b32_e32 v118, 0x1800, v118
	v_bfe_u32 v120, v114, 2, 11
	v_or3_b32 v118, v118, v120, v121
	v_and_b32_e32 v119, 0xffffff, v115
	v_lshlrev_b64 v[118:119], 8, v[118:119]
	v_lshl_add_u64 v[118:119], v[14:15], 0, v[118:119]
	global_load_dwordx4 v[136:139], v[118:119], off
	v_lshlrev_b32_e32 v118, 9, v114
	v_and_b32_e32 v118, 0x1e00, v118
	v_bfe_u32 v120, v114, 4, 9
	v_or3_b32 v118, v118, v120, v121
	v_and_b32_e32 v119, 0xffffff, v115
	v_lshlrev_b64 v[118:119], 8, v[118:119]
	v_lshl_add_u64 v[118:119], v[16:17], 0, v[118:119]
	global_load_dwordx4 v[140:143], v[118:119], off
	s_add_i32 s1, s12, 3
	s_min_i32 s4, s1, s0
	s_ashr_i32 s5, s4, 31
	v_lshl_add_u64 v[162:163], s[4:5], 3, v[10:11]
	v_lshl_add_u64 v[164:165], v[162:163], 4, s[16:17]
	v_lshl_add_u64 v[164:165], v[164:165], 0, v[158:159]
	global_load_dword v170, v[164:165], off
	v_lshl_add_u64 v[166:167], v[164:165], 0, s[98:99]
	global_load_dword v171, v[166:167], off
	v_lshl_add_u64 v[166:167], v[164:165], 0, s[100:101]
	global_load_dword v172, v[166:167], off
	v_lshlrev_b64 v[166:167], 8, v[162:163]
	v_lshl_add_u64 v[166:167], v[12:13], 0, v[166:167]
	global_load_dwordx4 v[180:183], v[166:167], off
	v_and_b32_e32 v169, 0xffffe000, v162
	v_lshlrev_b32_e32 v166, 11, v162
	v_and_b32_e32 v166, 0x1800, v166
	v_bfe_u32 v168, v162, 2, 11
	v_or3_b32 v166, v166, v168, v169
	v_and_b32_e32 v167, 0xffffff, v163
	v_lshlrev_b64 v[166:167], 8, v[166:167]
	v_lshl_add_u64 v[166:167], v[14:15], 0, v[166:167]
	global_load_dwordx4 v[184:187], v[166:167], off
	v_lshlrev_b32_e32 v166, 9, v162
	v_and_b32_e32 v166, 0x1e00, v166
	v_bfe_u32 v168, v162, 4, 9
	v_or3_b32 v166, v166, v168, v169
	v_and_b32_e32 v167, 0xffffff, v163
	v_lshlrev_b64 v[166:167], 8, v[166:167]
	v_lshl_add_u64 v[166:167], v[16:17], 0, v[166:167]
	global_load_dwordx4 v[188:191], v[166:167], off
	s_add_i32 s12, s12, 4
	s_waitcnt vmcnt(18)
; __device__ __forceinline__ float bf2f(unsigned h) { return __uint_as_float(h << 16); }
; __device__ __forceinline__ unsigned pk2(float lo, float hi) { return pg8::cvt_pk_bf16(lo, hi); }
; __device__ __forceinline__ void dil_merge_units(const Ctx& X, const bf16* H, bf16* Y, int u0, int u1) {
;     const float* LSE = (const float*)(X.ws + WS_LSE);
;     for (int ub = u0; ub < u1; ub += 4)
; #pragma unroll
;     for (int p = 0; p < 4; ++p) { const int un = min(ub + p, u1 - 1); const int slot = (X.tid >> 4) & 3, c8 = X.tid & 15; const size_t m = (size_t)un * 8 + (X.tid >> 6);
;         const float l0 = LSE[(0 * (size_t)M + m) * 4 + slot], l1 = LSE[(1 * (size_t)M + m) * 4 + slot], l2 = LSE[(2 * (size_t)M + m) * 4 + slot]; const float mxl = fmaxf(l0, fmaxf(l1, l2));
;         const float e0 = __expf(l0 - mxl), e1 = __expf(l1 - mxl), e2 = __expf(l2 - mxl), inv = __builtin_amdgcn_rcpf(e0 + e1 + e2); const float w[3] = {e0 * inv, e1 * inv, e2 * inv};
;         float acc[8];
; #pragma unroll
;         for (int e = 0; e < 8; ++e) acc[e] = 0.f;
; #pragma unroll
;         for (int g = 0; g < 3; ++g) { const int sh = 2 * g, t = (int)(m & 8191); const size_t pm = (m & ~(size_t)8191) + (size_t)(((t & ((1 << sh) - 1)) << (13 - sh)) + (t >> sh));
;             const v4u ow = *(const v4u*)hptr(H, pm, C_DIL + (3 * g) * 512 + slot * 128 + 8 * c8);
;             acc[0] += w[g] * bf2f(ow.x & 0xffffu); acc[1] += w[g] * bf2f(ow.x >> 16); acc[2] += w[g] * bf2f(ow.y & 0xffffu); acc[3] += w[g] * bf2f(ow.y >> 16);
;             acc[4] += w[g] * bf2f(ow.z & 0xffffu); acc[5] += w[g] * bf2f(ow.z >> 16); acc[6] += w[g] * bf2f(ow.w & 0xffffu); acc[7] += w[g] * bf2f(ow.w >> 16); }
;         v4u o; o.x = pk2(acc[0], acc[1]); o.y = pk2(acc[2], acc[3]); o.z = pk2(acc[4], acc[5]); o.w = pk2(acc[6], acc[7]);
;         *(v4u*)(Y + m * D + 1536 + slot * 128 + 8 * c8) = o; }
; }
	v_max3_f32 v47, v44, v45, v46
	v_sub_f32_e32 v44, v44, v47
	v_sub_f32_e32 v45, v45, v47
	v_mul_f32_e32 v44, 0x3fb8aa3b, v44
	v_mul_f32_e32 v45, 0x3fb8aa3b, v45
	v_sub_f32_e32 v46, v46, v47
	v_exp_f32_e32 v44, v44
	v_exp_f32_e32 v45, v45
	v_mul_f32_e32 v46, 0x3fb8aa3b, v46
	v_exp_f32_e32 v46, v46
	s_nop 0
	v_add_f32_e32 v47, v44, v45
	v_add_f32_e32 v47, v46, v47
	v_rcp_f32_e32 v47, v47
	s_nop 0
	v_mul_f32_e32 v48, v44, v47
	v_mul_f32_e32 v50, v45, v47
	v_mul_f32_e32 v52, v46, v47
	v_lshlrev_b32_e32 v46, 16, v54
	v_and_b32_e32 v47, 0xffff0000, v54
	v_pk_fma_f32 v[38:39], v[48:49], v[46:47], 0 op_sel_hi:[0,1,0]
	v_lshlrev_b32_e32 v46, 16, v58
	v_and_b32_e32 v47, 0xffff0000, v58
	v_pk_fma_f32 v[38:39], v[50:51], v[46:47], v[38:39] op_sel_hi:[0,1,1]
	v_lshlrev_b32_e32 v46, 16, v62
	v_and_b32_e32 v47, 0xffff0000, v62
	v_pk_fma_f32 v[38:39], v[52:53], v[46:47], v[38:39] op_sel_hi:[0,1,1]
	v_lshlrev_b32_e32 v46, 16, v55
	v_and_b32_e32 v47, 0xffff0000, v55
	v_pk_fma_f32 v[40:41], v[48:49], v[46:47], 0 op_sel_hi:[0,1,0]
	v_lshlrev_b32_e32 v46, 16, v59
	v_and_b32_e32 v47, 0xffff0000, v59
	v_pk_fma_f32 v[40:41], v[50:51], v[46:47], v[40:41] op_sel_hi:[0,1,1]
	v_lshlrev_b32_e32 v46, 16, v63
	v_and_b32_e32 v47, 0xffff0000, v63
	v_pk_fma_f32 v[40:41], v[52:53], v[46:47], v[40:41] op_sel_hi:[0,1,1]
	v_lshlrev_b32_e32 v46, 16, v56
	v_and_b32_e32 v47, 0xffff0000, v56
	v_pk_fma_f32 v[42:43], v[48:49], v[46:47], 0 op_sel_hi:[0,1,0]
	v_lshlrev_b32_e32 v46, 16, v60
	v_and_b32_e32 v47, 0xffff0000, v60
	v_pk_fma_f32 v[42:43], v[50:51], v[46:47], v[42:43] op_sel_hi:[0,1,1]
	v_lshlrev_b32_e32 v46, 16, v64
	v_and_b32_e32 v47, 0xffff0000, v64
	v_pk_fma_f32 v[42:43], v[52:53], v[46:47], v[42:43] op_sel_hi:[0,1,1]
	v_lshlrev_b32_e32 v46, 16, v57
	v_and_b32_e32 v47, 0xffff0000, v57
	v_pk_fma_f32 v[44:45], v[48:49], v[46:47], 0 op_sel_hi:[0,1,0]
	v_lshlrev_b32_e32 v46, 16, v61
	v_and_b32_e32 v47, 0xffff0000, v61
	v_pk_fma_f32 v[44:45], v[50:51], v[46:47], v[44:45] op_sel_hi:[0,1,1]
	v_lshlrev_b32_e32 v46, 16, v65
	v_and_b32_e32 v47, 0xffff0000, v65
	v_pk_fma_f32 v[44:45], v[52:53], v[46:47], v[44:45] op_sel_hi:[0,1,1]
	v_cvt_pk_bf16_f32 v54, v38, v39
	v_cvt_pk_bf16_f32 v55, v40, v41
	v_cvt_pk_bf16_f32 v56, v42, v43
	v_cvt_pk_bf16_f32 v57, v44, v45
	v_lshlrev_b64 v[46:47], 12, v[36:37]
	v_lshl_add_u64 v[46:47], v[18:19], 0, v[46:47]
	global_store_dwordx4 v[46:47], v[54:57], off offset:3072
	s_waitcnt vmcnt(13)
	v_max3_f32 v77, v74, v75, v76
	v_sub_f32_e32 v74, v74, v77
	v_sub_f32_e32 v75, v75, v77
	v_mul_f32_e32 v74, 0x3fb8aa3b, v74
	v_mul_f32_e32 v75, 0x3fb8aa3b, v75
	v_sub_f32_e32 v76, v76, v77
	v_exp_f32_e32 v74, v74
	v_exp_f32_e32 v75, v75
	v_mul_f32_e32 v76, 0x3fb8aa3b, v76
	v_exp_f32_e32 v76, v76
	s_nop 0
	v_add_f32_e32 v77, v74, v75
	v_add_f32_e32 v77, v76, v77
	v_rcp_f32_e32 v77, v77
	s_nop 0
	v_mul_f32_e32 v78, v74, v77
	v_mul_f32_e32 v80, v75, v77
	v_mul_f32_e32 v82, v76, v77
	v_lshlrev_b32_e32 v76, 16, v84
	v_and_b32_e32 v77, 0xffff0000, v84
	v_pk_fma_f32 v[68:69], v[78:79], v[76:77], 0 op_sel_hi:[0,1,0]
	v_lshlrev_b32_e32 v76, 16, v88
	v_and_b32_e32 v77, 0xffff0000, v88
	v_pk_fma_f32 v[68:69], v[80:81], v[76:77], v[68:69] op_sel_hi:[0,1,1]
	v_lshlrev_b32_e32 v76, 16, v92
	v_and_b32_e32 v77, 0xffff0000, v92
	v_pk_fma_f32 v[68:69], v[82:83], v[76:77], v[68:69] op_sel_hi:[0,1,1]
	v_lshlrev_b32_e32 v76, 16, v85
	v_and_b32_e32 v77, 0xffff0000, v85
	v_pk_fma_f32 v[70:71], v[78:79], v[76:77], 0 op_sel_hi:[0,1,0]
	v_lshlrev_b32_e32 v76, 16, v89
	v_and_b32_e32 v77, 0xffff0000, v89
	v_pk_fma_f32 v[70:71], v[80:81], v[76:77], v[70:71] op_sel_hi:[0,1,1]
	v_lshlrev_b32_e32 v76, 16, v93
	v_and_b32_e32 v77, 0xffff0000, v93
	v_pk_fma_f32 v[70:71], v[82:83], v[76:77], v[70:71] op_sel_hi:[0,1,1]
	v_lshlrev_b32_e32 v76, 16, v86
	v_and_b32_e32 v77, 0xffff0000, v86
	v_pk_fma_f32 v[72:73], v[78:79], v[76:77], 0 op_sel_hi:[0,1,0]
	v_lshlrev_b32_e32 v76, 16, v90
	v_and_b32_e32 v77, 0xffff0000, v90
	v_pk_fma_f32 v[72:73], v[80:81], v[76:77], v[72:73] op_sel_hi:[0,1,1]
	v_lshlrev_b32_e32 v76, 16, v94
	v_and_b32_e32 v77, 0xffff0000, v94
	v_pk_fma_f32 v[72:73], v[82:83], v[76:77], v[72:73] op_sel_hi:[0,1,1]
	v_lshlrev_b32_e32 v76, 16, v87
	v_and_b32_e32 v77, 0xffff0000, v87
	v_pk_fma_f32 v[74:75], v[78:79], v[76:77], 0 op_sel_hi:[0,1,0]
	v_lshlrev_b32_e32 v76, 16, v91
	v_and_b32_e32 v77, 0xffff0000, v91
	v_pk_fma_f32 v[74:75], v[80:81], v[76:77], v[74:75] op_sel_hi:[0,1,1]
	v_lshlrev_b32_e32 v76, 16, v95
	v_and_b32_e32 v77, 0xffff0000, v95
	v_pk_fma_f32 v[74:75], v[82:83], v[76:77], v[74:75] op_sel_hi:[0,1,1]
	v_cvt_pk_bf16_f32 v84, v68, v69
	v_cvt_pk_bf16_f32 v85, v70, v71
	v_cvt_pk_bf16_f32 v86, v72, v73
	v_cvt_pk_bf16_f32 v87, v74, v75
	v_lshlrev_b64 v[76:77], 12, v[66:67]
	v_lshl_add_u64 v[76:77], v[18:19], 0, v[76:77]
	global_store_dwordx4 v[76:77], v[84:87], off offset:3072
	s_waitcnt vmcnt(8)
; __device__ __forceinline__ float bf2f(unsigned h) { return __uint_as_float(h << 16); }
; __device__ __forceinline__ unsigned pk2(float lo, float hi) { return pg8::cvt_pk_bf16(lo, hi); }
; __device__ __forceinline__ void dil_merge_units(const Ctx& X, const bf16* H, bf16* Y, int u0, int u1) {
;     const float* LSE = (const float*)(X.ws + WS_LSE);
;     for (int ub = u0; ub < u1; ub += 4)
; #pragma unroll
;     for (int p = 0; p < 4; ++p) { const int un = min(ub + p, u1 - 1); const int slot = (X.tid >> 4) & 3, c8 = X.tid & 15; const size_t m = (size_t)un * 8 + (X.tid >> 6);
;         const float l0 = LSE[(0 * (size_t)M + m) * 4 + slot], l1 = LSE[(1 * (size_t)M + m) * 4 + slot], l2 = LSE[(2 * (size_t)M + m) * 4 + slot]; const float mxl = fmaxf(l0, fmaxf(l1, l2));
;         const float e0 = __expf(l0 - mxl), e1 = __expf(l1 - mxl), e2 = __expf(l2 - mxl), inv = __builtin_amdgcn_rcpf(e0 + e1 + e2); const float w[3] = {e0 * inv, e1 * inv, e2 * inv};
;         float acc[8];
; #pragma unroll
;         for (int e = 0; e < 8; ++e) acc[e] = 0.f;
; #pragma unroll
;         for (int g = 0; g < 3; ++g) { const int sh = 2 * g, t = (int)(m & 8191); const size_t pm = (m & ~(size_t)8191) + (size_t)(((t & ((1 << sh) - 1)) << (13 - sh)) + (t >> sh));
;             const v4u ow = *(const v4u*)hptr(H, pm, C_DIL + (3 * g) * 512 + slot * 128 + 8 * c8);
;             acc[0] += w[g] * bf2f(ow.x & 0xffffu); acc[1] += w[g] * bf2f(ow.x >> 16); acc[2] += w[g] * bf2f(ow.y & 0xffffu); acc[3] += w[g] * bf2f(ow.y >> 16);
;             acc[4] += w[g] * bf2f(ow.z & 0xffffu); acc[5] += w[g] * bf2f(ow.z >> 16); acc[6] += w[g] * bf2f(ow.w & 0xffffu); acc[7] += w[g] * bf2f(ow.w >> 16); }
;         v4u o; o.x = pk2(acc[0], acc[1]); o.y = pk2(acc[2], acc[3]); o.z = pk2(acc[4], acc[5]); o.w = pk2(acc[6], acc[7]);
;         *(v4u*)(Y + m * D + 1536 + slot * 128 + 8 * c8) = o; }
; }
	v_max3_f32 v125, v122, v123, v124
	v_sub_f32_e32 v122, v122, v125
	v_sub_f32_e32 v123, v123, v125
	v_mul_f32_e32 v122, 0x3fb8aa3b, v122
	v_mul_f32_e32 v123, 0x3fb8aa3b, v123
	v_sub_f32_e32 v124, v124, v125
	v_exp_f32_e32 v122, v122
	v_exp_f32_e32 v123, v123
	v_mul_f32_e32 v124, 0x3fb8aa3b, v124
	v_exp_f32_e32 v124, v124
	s_nop 0
	v_add_f32_e32 v125, v122, v123
	v_add_f32_e32 v125, v124, v125
	v_rcp_f32_e32 v125, v125
	s_nop 0
	v_mul_f32_e32 v126, v122, v125
	v_mul_f32_e32 v128, v123, v125
	v_mul_f32_e32 v130, v124, v125
	v_lshlrev_b32_e32 v124, 16, v132
	v_and_b32_e32 v125, 0xffff0000, v132
	v_pk_fma_f32 v[116:117], v[126:127], v[124:125], 0 op_sel_hi:[0,1,0]
	v_lshlrev_b32_e32 v124, 16, v136
	v_and_b32_e32 v125, 0xffff0000, v136
	v_pk_fma_f32 v[116:117], v[128:129], v[124:125], v[116:117] op_sel_hi:[0,1,1]
	v_lshlrev_b32_e32 v124, 16, v140
	v_and_b32_e32 v125, 0xffff0000, v140
	v_pk_fma_f32 v[116:117], v[130:131], v[124:125], v[116:117] op_sel_hi:[0,1,1]
	v_lshlrev_b32_e32 v124, 16, v133
	v_and_b32_e32 v125, 0xffff0000, v133
	v_pk_fma_f32 v[118:119], v[126:127], v[124:125], 0 op_sel_hi:[0,1,0]
	v_lshlrev_b32_e32 v124, 16, v137
	v_and_b32_e32 v125, 0xffff0000, v137
	v_pk_fma_f32 v[118:119], v[128:129], v[124:125], v[118:119] op_sel_hi:[0,1,1]
	v_lshlrev_b32_e32 v124, 16, v141
	v_and_b32_e32 v125, 0xffff0000, v141
	v_pk_fma_f32 v[118:119], v[130:131], v[124:125], v[118:119] op_sel_hi:[0,1,1]
	v_lshlrev_b32_e32 v124, 16, v134
	v_and_b32_e32 v125, 0xffff0000, v134
	v_pk_fma_f32 v[120:121], v[126:127], v[124:125], 0 op_sel_hi:[0,1,0]
	v_lshlrev_b32_e32 v124, 16, v138
	v_and_b32_e32 v125, 0xffff0000, v138
	v_pk_fma_f32 v[120:121], v[128:129], v[124:125], v[120:121] op_sel_hi:[0,1,1]
	v_lshlrev_b32_e32 v124, 16, v142
	v_and_b32_e32 v125, 0xffff0000, v142
	v_pk_fma_f32 v[120:121], v[130:131], v[124:125], v[120:121] op_sel_hi:[0,1,1]
	v_lshlrev_b32_e32 v124, 16, v135
	v_and_b32_e32 v125, 0xffff0000, v135
	v_pk_fma_f32 v[122:123], v[126:127], v[124:125], 0 op_sel_hi:[0,1,0]
	v_lshlrev_b32_e32 v124, 16, v139
	v_and_b32_e32 v125, 0xffff0000, v139
	v_pk_fma_f32 v[122:123], v[128:129], v[124:125], v[122:123] op_sel_hi:[0,1,1]
	v_lshlrev_b32_e32 v124, 16, v143
	v_and_b32_e32 v125, 0xffff0000, v143
	v_pk_fma_f32 v[122:123], v[130:131], v[124:125], v[122:123] op_sel_hi:[0,1,1]
	v_cvt_pk_bf16_f32 v132, v116, v117
	v_cvt_pk_bf16_f32 v133, v118, v119
	v_cvt_pk_bf16_f32 v134, v120, v121
	v_cvt_pk_bf16_f32 v135, v122, v123
	v_lshlrev_b64 v[124:125], 12, v[114:115]
	v_lshl_add_u64 v[124:125], v[18:19], 0, v[124:125]
	global_store_dwordx4 v[124:125], v[132:135], off offset:3072
	s_waitcnt vmcnt(3)
	v_max3_f32 v173, v170, v171, v172
	v_sub_f32_e32 v170, v170, v173
	v_sub_f32_e32 v171, v171, v173
	v_mul_f32_e32 v170, 0x3fb8aa3b, v170
	v_mul_f32_e32 v171, 0x3fb8aa3b, v171
	v_sub_f32_e32 v172, v172, v173
	v_exp_f32_e32 v170, v170
	v_exp_f32_e32 v171, v171
	v_mul_f32_e32 v172, 0x3fb8aa3b, v172
	v_exp_f32_e32 v172, v172
	s_nop 0
	v_add_f32_e32 v173, v170, v171
	v_add_f32_e32 v173, v172, v173
	v_rcp_f32_e32 v173, v173
	s_nop 0
	v_mul_f32_e32 v174, v170, v173
	v_mul_f32_e32 v176, v171, v173
	v_mul_f32_e32 v178, v172, v173
	v_lshlrev_b32_e32 v172, 16, v180
	v_and_b32_e32 v173, 0xffff0000, v180
	v_pk_fma_f32 v[164:165], v[174:175], v[172:173], 0 op_sel_hi:[0,1,0]
	v_lshlrev_b32_e32 v172, 16, v184
	v_and_b32_e32 v173, 0xffff0000, v184
	v_pk_fma_f32 v[164:165], v[176:177], v[172:173], v[164:165] op_sel_hi:[0,1,1]
	v_lshlrev_b32_e32 v172, 16, v188
	v_and_b32_e32 v173, 0xffff0000, v188
	v_pk_fma_f32 v[164:165], v[178:179], v[172:173], v[164:165] op_sel_hi:[0,1,1]
	v_lshlrev_b32_e32 v172, 16, v181
	v_and_b32_e32 v173, 0xffff0000, v181
	v_pk_fma_f32 v[166:167], v[174:175], v[172:173], 0 op_sel_hi:[0,1,0]
	v_lshlrev_b32_e32 v172, 16, v185
	v_and_b32_e32 v173, 0xffff0000, v185
	v_pk_fma_f32 v[166:167], v[176:177], v[172:173], v[166:167] op_sel_hi:[0,1,1]
	v_lshlrev_b32_e32 v172, 16, v189
	v_and_b32_e32 v173, 0xffff0000, v189
	v_pk_fma_f32 v[166:167], v[178:179], v[172:173], v[166:167] op_sel_hi:[0,1,1]
	v_lshlrev_b32_e32 v172, 16, v182
	v_and_b32_e32 v173, 0xffff0000, v182
	v_pk_fma_f32 v[168:169], v[174:175], v[172:173], 0 op_sel_hi:[0,1,0]
	v_lshlrev_b32_e32 v172, 16, v186
	v_and_b32_e32 v173, 0xffff0000, v186
	v_pk_fma_f32 v[168:169], v[176:177], v[172:173], v[168:169] op_sel_hi:[0,1,1]
	v_lshlrev_b32_e32 v172, 16, v190
	v_and_b32_e32 v173, 0xffff0000, v190
	v_pk_fma_f32 v[168:169], v[178:179], v[172:173], v[168:169] op_sel_hi:[0,1,1]
	v_lshlrev_b32_e32 v172, 16, v183
	v_and_b32_e32 v173, 0xffff0000, v183
	v_pk_fma_f32 v[170:171], v[174:175], v[172:173], 0 op_sel_hi:[0,1,0]
	v_lshlrev_b32_e32 v172, 16, v187
	v_and_b32_e32 v173, 0xffff0000, v187
	v_pk_fma_f32 v[170:171], v[176:177], v[172:173], v[170:171] op_sel_hi:[0,1,1]
	v_lshlrev_b32_e32 v172, 16, v191
	v_and_b32_e32 v173, 0xffff0000, v191
	v_pk_fma_f32 v[170:171], v[178:179], v[172:173], v[170:171] op_sel_hi:[0,1,1]
	v_cvt_pk_bf16_f32 v180, v164, v165
	v_cvt_pk_bf16_f32 v181, v166, v167
	v_cvt_pk_bf16_f32 v182, v168, v169
	v_cvt_pk_bf16_f32 v183, v170, v171
	v_lshlrev_b64 v[172:173], 12, v[162:163]
	v_lshl_add_u64 v[172:173], v[18:19], 0, v[172:173]
	global_store_dwordx4 v[172:173], v[180:183], off offset:3072
	s_cmp_ge_i32 s12, s18
	s_cbranch_scc0 .LBB0_413
